# next tile slot and K address setup moved ahead of the end-of-softmax barrier so the MFMA phase opens with the K reads
# speedup vs baseline: 1.0445x; 1.0037x over previous
; #define LAS3 __attribute__((address_space(3)))
; #define ATT_SB() __builtin_amdgcn_sched_barrier(0)
; #define ATT_VREAD(buf, ks, vso) do { _Pragma("unroll") for (int d0 = 0; d0 < ND; ++d0) { const lds_cptr vq_ = ((d0 & 1) ? vpo : vpe) + (vso) + (d0 >> 1) * 8192 + (ks) * 2048; \
;       const s16x4 lo = vtr(vq_), hi4 = vtr(vq_ + 1024); \
;       buf[d0] = (bf16x8){lo[0], lo[1], lo[2], lo[3], hi4[0], hi4[1], hi4[2], hi4[3]}; } } while (0)
; #define ATT_PVK_RD(buf, ks, vp) do { _Pragma("unroll") for (int d0 = 0; d0 < ND; ++d0) { \
;       o[d0] = __builtin_amdgcn_mfma_f32_32x32x16_bf16(__builtin_bit_cast(bf16x8, pw[ks]), buf[d0], o[d0], 0, 0, 0); ATT_VREAD1(buf, d0, (ks) + 2, vp); ATT_SB(); } } while (0)
; template <int MODE>
; __device__ __forceinline__ void attn_unit(const Tensors& T0, int ureq, int b, int hh, int qblk, LAS3 char* shm, const bool dummy = false) {
;     ...
;     float cb = 0.f; bool near = true;
;     if (MODE) { if (k0 + 63 - Q0 <= -91) { cb = cbL; near = false; } else if (k0 - (Q0 + 127) >= 91) { cb = cbR; near = false; } }
;     if (cb != curcb) { curcb = cb;
; #pragma unroll
;       for (int r = 0; r < 16; ++r) negm[r] = cb - mhat; }
;     f32x16 C0 = negm, C1 = negm;
;     if (!(ATT_ABL == 4 && dummy)) { const int kso = (i & 3) * SLOTB; const int vp = ((i - 1) & 3) * SLOTB;
;       bf16x8 kf[8];
; #pragma unroll
;       for (int d0 = 0; d0 < 2; ++d0) { kf[2 * d0] = *(const LAS3 bf16x8*)(kp[d0] + kso); kf[2 * d0 + 1] = *(const LAS3 bf16x8*)(kp[d0] + kso + 4096); }
;       if (i > 0) { ATT_VREAD(vB, 1, vp); }
;       ATT_SB();
;       if (i > 0) { ATT_PVK_RD(vA, 0, vp); }
;       C0 = __builtin_amdgcn_mfma_f32_32x32x16_bf16(kf[0], qr[0], negm, 0, 0, 0); C1 = __builtin_amdgcn_mfma_f32_32x32x16_bf16(kf[1], qr[0], negm, 0, 0, 0);
.Lm1_head2_g0:
	ds_read_b128 v[100:103], v104
	ds_read_b128 v[206:209], v104 offset:4096
	v_mfma_f32_32x32x16_bf16 v[48:63], v[96:99], v[156:159], v[48:63]
	v_add_u32_e32 v205, s99, v193
	v_add_u32_e32 v242, s99, v190
	v_add_u32_e32 v104, s18, v195
	ds_read_b64_tr_b16 v[156:157], v205 offset:20480
	ds_read_b64_tr_b16 v[158:159], v205 offset:21504
	ds_read_b128 v[210:213], v104
	ds_read_b128 v[214:217], v104 offset:4096
	v_mfma_f32_32x32x16_bf16 v[64:79], v[96:99], v[152:155], v[64:79]
	ds_read_b64_tr_b16 v[152:153], v242 offset:20480
	ds_read_b64_tr_b16 v[154:155], v242 offset:21504
	ds_read_b64_tr_b16 v[218:219], v205 offset:18432
	ds_read_b64_tr_b16 v[220:221], v205 offset:19456
	s_add_i32 s96, s93, -2
	s_add_i32 s8, s95, 0xffffff67
	v_mfma_f32_32x32x16_bf16 v[32:47], v[96:99], v[148:151], v[32:47]
	ds_read_b64_tr_b16 v[148:149], v205 offset:28672
	ds_read_b64_tr_b16 v[150:151], v205 offset:29696
	ds_read_b64_tr_b16 v[222:223], v242 offset:18432
	ds_read_b64_tr_b16 v[224:225], v242 offset:19456
	s_cmpk_gt_i32 s8, 0xff66
	s_cselect_b64 vcc, -1, 0
	s_cmpk_gt_i32 s8, 0xd9
	s_cselect_b64 s[8:9], -1, 0
	v_mfma_f32_32x32x16_bf16 v[16:31], v[96:99], v[144:147], v[16:31]
	ds_read_b64_tr_b16 v[144:145], v242 offset:28672
	ds_read_b64_tr_b16 v[146:147], v242 offset:29696
	ds_read_b64_tr_b16 v[226:227], v205 offset:26624
	ds_read_b64_tr_b16 v[228:229], v205 offset:27648
	ds_read_b64_tr_b16 v[230:231], v242 offset:26624
	ds_read_b64_tr_b16 v[232:233], v242 offset:27648
	v_cndmask_b32_e64 v250, 0, v192, s[8:9]
	v_cndmask_b32_e32 v204, v191, v250, vcc
	v_add_u32_e32 v248, s18, v193
	v_add_u32_e32 v249, s18, v190
	v_cmp_neq_f32_e64 s[8:9], v204, v201
	v_add_u32_e32 v238, s18, v197
	s_and_b64 vcc, exec, s[8:9]
	s_cbranch_vccz .Lm1_negm_keep
	v_sub_f32_e32 v80, v204, v202
	v_mov_b32_e32 v201, v204
	v_mov_b32_e32 v81, v80
	v_mov_b32_e32 v82, v80
	v_mov_b32_e32 v83, v80
	v_mov_b32_e32 v84, v80
	v_mov_b32_e32 v85, v80
	v_mov_b32_e32 v86, v80
	v_mov_b32_e32 v87, v80
	v_mov_b32_e32 v88, v80
	v_mov_b32_e32 v89, v80
	v_mov_b32_e32 v90, v80
	v_mov_b32_e32 v91, v80
	v_mov_b32_e32 v92, v80
	v_mov_b32_e32 v93, v80
	v_mov_b32_e32 v94, v80
	v_mov_b32_e32 v95, v80
	s_nop 0

; __device__ __forceinline__ unsigned cvtpk(float lo, float hi) { f32x2_t v = {lo, hi}; bf16x2_t b = __builtin_convertvector(v, bf16x2_t); return __builtin_bit_cast(unsigned, b); }
; #define ATT_BAR_V(full) do { if (full) { if (MODE) ATT_WAIT_BAR(4); else ATT_WAIT_BAR(2); } else ATT_WAIT_BAR(0); } while (0)
; #define ATT_BAR_L() asm volatile("s_waitcnt lgkmcnt(0)\n\ts_barrier" ::: "memory")
; template <int MODE>
; __device__ __forceinline__ void attn_unit(const Tensors& T0, int ureq, int b, int hh, int qblk, LAS3 char* shm, const bool dummy = false) {
;     ...
;     float sacc = 0.f;
; #pragma unroll
;     for (int r = 0; r < 16; ++r) { C0[r] = __builtin_amdgcn_exp2f(C0[r]); C1[r] = __builtin_amdgcn_exp2f(C1[r]); sacc += C0[r] + C1[r]; }
;     l_reg += sacc;
; #pragma unroll
;     for (int j = 0; j < 4; ++j) { pw[0][j] = cvtpk(C0[2 * j], C0[2 * j + 1]); pw[1][j] = cvtpk(C0[8 + 2 * j], C0[8 + 2 * j + 1]);
;                                   pw[2][j] = cvtpk(C1[2 * j], C1[2 * j + 1]); pw[3][j] = cvtpk(C1[8 + 2 * j], C1[8 + 2 * j + 1]); }
;     }
;     asm volatile("" : "+v"(pw[0]), "+v"(pw[1]), "+v"(pw[2]), "+v"(pw[3]), "+v"(l_reg));
;     if (grp == 0) ATT_BAR_V(i + 2 < NT); else if (i + 1 < NT) ATT_BAR_L();
;   }
.LBB0_125:
	v_exp_f32_e32 v112, v112
	v_exp_f32_e32 v160, v96
	v_exp_f32_e32 v96, v113
	v_exp_f32_e32 v97, v97
	v_exp_f32_e32 v114, v114
	v_exp_f32_e32 v98, v98
	v_exp_f32_e32 v115, v115
	v_exp_f32_e32 v99, v99
	v_add_f32_e32 v113, v160, v112
	v_exp_f32_e32 v116, v116
	v_exp_f32_e32 v100, v100
	v_add_f32_e32 v161, v97, v96
	v_exp_f32_e32 v117, v117
	v_exp_f32_e32 v101, v101
	v_add_f32_e32 v113, v161, v113
	v_add_f32_e32 v161, v98, v114
	v_exp_f32_e32 v118, v118
	v_exp_f32_e32 v102, v102
	v_add_f32_e32 v113, v161, v113
	v_add_f32_e32 v161, v99, v115
	v_exp_f32_e32 v119, v119
	v_exp_f32_e32 v103, v103
	v_add_f32_e32 v113, v161, v113
	v_add_f32_e32 v161, v100, v116
	v_exp_f32_e32 v120, v120
	v_exp_f32_e32 v104, v104
	v_add_f32_e32 v113, v161, v113
	v_add_f32_e32 v161, v101, v117
	v_exp_f32_e32 v121, v121
	v_exp_f32_e32 v105, v105
	v_add_f32_e32 v113, v161, v113
	v_add_f32_e32 v161, v102, v118
	v_exp_f32_e32 v122, v122
	v_exp_f32_e32 v106, v106
	v_add_f32_e32 v113, v161, v113
	v_add_f32_e32 v161, v103, v119
	v_exp_f32_e32 v123, v123
	v_exp_f32_e32 v107, v107
	v_add_f32_e32 v113, v161, v113
	v_add_f32_e32 v161, v104, v120
	v_exp_f32_e32 v124, v124
	v_exp_f32_e32 v108, v108
	v_add_f32_e32 v113, v161, v113
	v_add_f32_e32 v161, v105, v121
	v_exp_f32_e32 v125, v125
	v_exp_f32_e32 v109, v109
	v_add_f32_e32 v113, v161, v113
	v_add_f32_e32 v161, v106, v122
	v_exp_f32_e32 v126, v126
	v_exp_f32_e32 v110, v110
	v_add_f32_e32 v113, v161, v113
	v_add_f32_e32 v161, v107, v123
	v_exp_f32_e32 v127, v127
	v_exp_f32_e32 v111, v111
	v_add_f32_e32 v113, v161, v113
	v_add_f32_e32 v161, v108, v124
	v_add_f32_e32 v113, v161, v113
	v_add_f32_e32 v161, v109, v125
	v_add_f32_e32 v113, v161, v113
	v_add_f32_e32 v161, v110, v126
	v_add_f32_e32 v113, v161, v113
	v_add_f32_e32 v161, v111, v127
	v_add_f32_e32 v113, v161, v113
	v_cvt_pk_bf16_f32 v96, v112, v96
	v_cvt_pk_bf16_f32 v168, v120, v121
	v_cvt_pk_bf16_f32 v164, v160, v97
	v_cvt_pk_bf16_f32 v160, v104, v105
	v_cvt_pk_bf16_f32 v97, v114, v115
	v_cvt_pk_bf16_f32 v169, v122, v123
	v_cvt_pk_bf16_f32 v165, v98, v99
	v_cvt_pk_bf16_f32 v161, v106, v107
	v_cvt_pk_bf16_f32 v98, v116, v117
	v_cvt_pk_bf16_f32 v170, v124, v125
	v_cvt_pk_bf16_f32 v166, v100, v101
	v_cvt_pk_bf16_f32 v162, v108, v109
	v_cvt_pk_bf16_f32 v99, v118, v119
	v_cvt_pk_bf16_f32 v171, v126, v127
	v_cvt_pk_bf16_f32 v167, v102, v103
	v_cvt_pk_bf16_f32 v163, v110, v111
	v_add_f32_e32 v198, v198, v113
	s_add_i32 s93, s93, 1
	s_add_i32 s8, s94, s93
	s_add_i32 s95, s95, 64
	s_add_u32 s100, s100, s68
	s_addc_u32 s101, s101, s69
	v_add_u32_e32 v203, 0x100, v203
	s_mov_b32 s98, s97
	s_add_i32 s18, s98, 0xffff0000
	s_and_b32 s18, s18, 0x18000
	v_add_u32_e32 v104, s18, v194
	s_add_i32 s97, s98, 0x8000
	s_and_b32 s99, s97, 0x18000
	s_cmp_ge_u32 s96, s82
	s_cbranch_scc1 .Lm1_B_drain_g0
	s_waitcnt vmcnt(4) lgkmcnt(0)
	s_setprio 1
	s_barrier
	s_branch .Lm1_head2_g0
.Lm1_B_drain_g0:
	s_waitcnt vmcnt(0) lgkmcnt(0)
	s_barrier
	s_cmp_eq_u32 s8, 2
	s_cbranch_scc1 .LBB0_136
	s_setprio 1
	s_branch .Lm1_head2_g0

; __device__ __forceinline__ unsigned cvtpk(float lo, float hi) { f32x2_t v = {lo, hi}; bf16x2_t b = __builtin_convertvector(v, bf16x2_t); return __builtin_bit_cast(unsigned, b); }
; #define ATT_BAR_V(full) do { if (full) { if (MODE) ATT_WAIT_BAR(4); else ATT_WAIT_BAR(2); } else ATT_WAIT_BAR(0); } while (0)
; #define ATT_BAR_L() asm volatile("s_waitcnt lgkmcnt(0)\n\ts_barrier" ::: "memory")
; template <int MODE>
; __device__ __forceinline__ void attn_unit(const Tensors& T0, int ureq, int b, int hh, int qblk, LAS3 char* shm, const bool dummy = false) {
;     ...
;     float sacc = 0.f;
; #pragma unroll
;     for (int r = 0; r < 16; ++r) { C0[r] = __builtin_amdgcn_exp2f(C0[r]); C1[r] = __builtin_amdgcn_exp2f(C1[r]); sacc += C0[r] + C1[r]; }
;     l_reg += sacc;
; #pragma unroll
;     for (int j = 0; j < 4; ++j) { pw[0][j] = cvtpk(C0[2 * j], C0[2 * j + 1]); pw[1][j] = cvtpk(C0[8 + 2 * j], C0[8 + 2 * j + 1]);
;                                   pw[2][j] = cvtpk(C1[2 * j], C1[2 * j + 1]); pw[3][j] = cvtpk(C1[8 + 2 * j], C1[8 + 2 * j + 1]); }
;     }
;     asm volatile("" : "+v"(pw[0]), "+v"(pw[1]), "+v"(pw[2]), "+v"(pw[3]), "+v"(l_reg));
;     if (grp == 0) ATT_BAR_V(i + 2 < NT); else if (i + 1 < NT) ATT_BAR_L();
;   }
.Lm1g1_125:
	v_exp_f32_e32 v112, v112
	v_exp_f32_e32 v160, v96
	v_exp_f32_e32 v96, v113
	v_exp_f32_e32 v97, v97
	v_exp_f32_e32 v114, v114
	v_exp_f32_e32 v98, v98
	v_exp_f32_e32 v115, v115
	v_exp_f32_e32 v99, v99
	v_add_f32_e32 v113, v160, v112
	v_exp_f32_e32 v116, v116
	v_exp_f32_e32 v100, v100
	v_add_f32_e32 v161, v97, v96
	v_exp_f32_e32 v117, v117
	v_exp_f32_e32 v101, v101
	v_add_f32_e32 v113, v161, v113
	v_add_f32_e32 v161, v98, v114
	v_exp_f32_e32 v118, v118
	v_exp_f32_e32 v102, v102
	v_add_f32_e32 v113, v161, v113
	v_add_f32_e32 v161, v99, v115
	v_exp_f32_e32 v119, v119
	v_exp_f32_e32 v103, v103
	v_add_f32_e32 v113, v161, v113
	v_add_f32_e32 v161, v100, v116
	v_exp_f32_e32 v120, v120
	v_exp_f32_e32 v104, v104
	v_add_f32_e32 v113, v161, v113
	v_add_f32_e32 v161, v101, v117
	v_exp_f32_e32 v121, v121
	v_exp_f32_e32 v105, v105
	v_add_f32_e32 v113, v161, v113
	v_add_f32_e32 v161, v102, v118
	v_exp_f32_e32 v122, v122
	v_exp_f32_e32 v106, v106
	v_add_f32_e32 v113, v161, v113
	v_add_f32_e32 v161, v103, v119
	v_exp_f32_e32 v123, v123
	v_exp_f32_e32 v107, v107
	v_add_f32_e32 v113, v161, v113
	v_add_f32_e32 v161, v104, v120
	v_exp_f32_e32 v124, v124
	v_exp_f32_e32 v108, v108
	v_add_f32_e32 v113, v161, v113
	v_add_f32_e32 v161, v105, v121
	v_exp_f32_e32 v125, v125
	v_exp_f32_e32 v109, v109
	v_add_f32_e32 v113, v161, v113
	v_add_f32_e32 v161, v106, v122
	v_exp_f32_e32 v126, v126
	v_exp_f32_e32 v110, v110
	v_add_f32_e32 v113, v161, v113
	v_add_f32_e32 v161, v107, v123
	v_exp_f32_e32 v127, v127
	v_exp_f32_e32 v111, v111
	v_add_f32_e32 v113, v161, v113
	v_add_f32_e32 v161, v108, v124
	v_add_f32_e32 v113, v161, v113
	v_add_f32_e32 v161, v109, v125
	v_add_f32_e32 v113, v161, v113
	v_add_f32_e32 v161, v110, v126
	v_add_f32_e32 v113, v161, v113
	v_add_f32_e32 v161, v111, v127
	v_add_f32_e32 v113, v161, v113
	v_cvt_pk_bf16_f32 v96, v112, v96
	v_cvt_pk_bf16_f32 v168, v120, v121
	v_cvt_pk_bf16_f32 v164, v160, v97
	v_cvt_pk_bf16_f32 v160, v104, v105
	v_cvt_pk_bf16_f32 v97, v114, v115
	v_cvt_pk_bf16_f32 v169, v122, v123
	v_cvt_pk_bf16_f32 v165, v98, v99
	v_cvt_pk_bf16_f32 v161, v106, v107
	v_cvt_pk_bf16_f32 v98, v116, v117
	v_cvt_pk_bf16_f32 v170, v124, v125
	v_cvt_pk_bf16_f32 v166, v100, v101
	v_cvt_pk_bf16_f32 v162, v108, v109
	v_cvt_pk_bf16_f32 v99, v118, v119
	v_cvt_pk_bf16_f32 v171, v126, v127
	v_cvt_pk_bf16_f32 v167, v102, v103
	v_cvt_pk_bf16_f32 v163, v110, v111
	v_add_f32_e32 v198, v198, v113
	s_add_i32 s93, s93, 1
	s_add_i32 s8, s94, s93
	s_add_i32 s95, s95, 64
	s_add_u32 s100, s100, s68
	s_addc_u32 s101, s101, s69
	v_add_u32_e32 v203, 0x100, v203
	s_mov_b32 s98, s97
	s_add_i32 s18, s98, 0xffff0000
	s_and_b32 s18, s18, 0x18000
	v_add_u32_e32 v104, s18, v194
	s_add_i32 s97, s98, 0x8000
	s_and_b32 s99, s97, 0x18000
	s_cmp_ge_u32 s96, s83
	s_cbranch_scc1 .LBB0_136
	s_waitcnt lgkmcnt(0)
	s_setprio 1
	s_barrier
	s_branch .Lm1_head2_g1
